# LN epilogues: final X/H (and y) stores transposed through the dead LDS ring so each store instruction writes whole row pieces (4x256 B / 8x128 B) instead of 16 scattered rows
# speedup vs baseline: 1.0900x; 1.0900x over previous
.Lln1_pok1:
	v_add_f32_e32 v250, v250, v226
	v_add_f32_e32 v252, v252, v228
	v_add_f32_e32 v250, v250, v230
	v_add_f32_e32 v252, v252, v232
	v_add_f32_e32 v250, v250, v234
	v_add_f32_e32 v252, v252, v236
	v_add_f32_e32 v250, v250, v238
	v_add_f32_e32 v252, v252, v240
	v_add_f32_e32 v250, v250, v206
	v_add_f32_e32 v252, v252, v208
	v_add_f32_e32 v250, v250, v210
	v_add_f32_e32 v252, v252, v212
	v_add_f32_e32 v250, v250, v214
	v_add_f32_e32 v252, v252, v216
	v_add_f32_e32 v250, v250, v218
	v_add_f32_e32 v252, v252, v220
	global_load_dwordx4 v[226:229], v246, s[22:23]
	global_load_dwordx4 v[230:233], v246, s[22:23] offset:64
	global_load_dwordx4 v[234:237], v246, s[22:23] offset:128
	global_load_dwordx4 v[238:241], v246, s[22:23] offset:192
	v_mov_b32_e32 v206, v250
	v_mov_b32_e32 v207, v252
	v_mul_f32_e32 v208, 0x3a800000, v206
	v_mul_f32_e32 v209, v208, v208
	v_mov_b32_e32 v216, 0x3a800000
	v_fma_f32 v209, v207, v216, -v209
	v_max_f32_e32 v209, 0, v209
	v_add_f32_e32 v209, 0x3727c5ac, v209
	v_rsq_f32_e32 v209, v209
	v_mov_b32_e32 v210, v208
	v_mov_b32_e32 v211, v208
	v_mov_b32_e32 v214, v209
	v_mov_b32_e32 v215, v209
	s_nop 1
	v_permlane16_swap_b32_e32 v210, v211
	v_permlane16_swap_b32_e32 v214, v215
	v_mov_b32_e32 v212, v210
	v_mov_b32_e32 v213, v211
	v_mov_b32_e32 v216, v214
	v_mov_b32_e32 v217, v215
	s_nop 1
	v_permlane32_swap_b32_e32 v210, v212
	v_permlane32_swap_b32_e32 v211, v213
	v_permlane32_swap_b32_e32 v214, v216
	v_permlane32_swap_b32_e32 v215, v217
	v_readfirstlane_b32 s64, v137
	s_lshr_b32 s64, s64, 6
	s_lshl_b32 s64, s64, 14
	v_and_b32_e32 v222, 63, v137
	v_and_b32_e32 v246, 15, v222
	v_lshrrev_b32_e32 v247, 4, v222
	v_and_b32_e32 v248, 3, v246
	v_xor_b32_e32 v248, v248, v247
	v_lshlrev_b32_e32 v248, 4, v248
	v_lshl_add_u32 v248, v246, 8, v248
	v_add_u32_e32 v248, s64, v248
	v_lshl_add_u32 v249, v222, 4, s64
	v_add_u32_e32 v250, s36, v247
	v_lshlrev_b32_e32 v250, 12, v250
	v_xor_b32_e32 v251, v246, v247
	v_lshl_add_u32 v250, v251, 4, v250
	s_lshl_b32 s65, s37, 2
	v_add_u32_e32 v250, s65, v250
	v_sub_f32_e32 v62, v62, v210
	v_sub_f32_e32 v63, v63, v210
	v_sub_f32_e32 v64, v64, v210
	v_sub_f32_e32 v65, v65, v210
	v_mul_f32_e32 v62, v214, v62
	v_mul_f32_e32 v63, v214, v63
	v_mul_f32_e32 v64, v214, v64
	v_mul_f32_e32 v65, v214, v65
	v_fma_f32 v62, v66, v62, v90
	v_fma_f32 v63, v67, v63, v91
	v_fma_f32 v64, v68, v64, v92
	v_fma_f32 v65, v69, v65, v93
	ds_write_b128 v248, v[62:65] offset:0
	v_sub_f32_e32 v86, v86, v210
	v_sub_f32_e32 v87, v87, v210
	v_sub_f32_e32 v88, v88, v210
	v_sub_f32_e32 v89, v89, v210
	v_mul_f32_e32 v86, v214, v86
	v_mul_f32_e32 v87, v214, v87
	v_mul_f32_e32 v88, v214, v88
	v_mul_f32_e32 v89, v214, v89
	v_fma_f32 v86, v74, v86, v94
	v_fma_f32 v87, v75, v87, v95
	v_fma_f32 v88, v76, v88, v96
	v_fma_f32 v89, v77, v89, v97
	ds_write_b128 v248, v[86:89] offset:64
	v_sub_f32_e32 v70, v70, v210
	v_sub_f32_e32 v71, v71, v210
	v_sub_f32_e32 v72, v72, v210
	v_sub_f32_e32 v73, v73, v210
	v_mul_f32_e32 v70, v214, v70
	v_mul_f32_e32 v71, v214, v71
	v_mul_f32_e32 v72, v214, v72
	v_mul_f32_e32 v73, v214, v73
	v_fma_f32 v70, v78, v70, v108
	v_fma_f32 v71, v79, v71, v109
	v_fma_f32 v72, v80, v72, v110
	v_fma_f32 v73, v81, v73, v111
	ds_write_b128 v248, v[70:73] offset:128
	v_sub_f32_e32 v176, v176, v210
	v_sub_f32_e32 v177, v177, v210
	v_sub_f32_e32 v178, v178, v210
	v_sub_f32_e32 v179, v179, v210
	v_mul_f32_e32 v176, v214, v176
	v_mul_f32_e32 v177, v214, v177
	v_mul_f32_e32 v178, v214, v178
	v_mul_f32_e32 v179, v214, v179
	v_fma_f32 v176, v82, v176, v172
	v_fma_f32 v177, v83, v177, v173
	v_fma_f32 v178, v84, v178, v174
	v_fma_f32 v179, v85, v179, v175
	ds_write_b128 v248, v[176:179] offset:192
	v_sub_f32_e32 v202, v202, v211
	v_sub_f32_e32 v203, v203, v211
	v_sub_f32_e32 v204, v204, v211
	v_sub_f32_e32 v205, v205, v211
	v_mul_f32_e32 v202, v215, v202
	v_mul_f32_e32 v203, v215, v203
	v_mul_f32_e32 v204, v215, v204
	v_mul_f32_e32 v205, v215, v205
	v_fma_f32 v202, v66, v202, v90
	v_fma_f32 v203, v67, v203, v91
	v_fma_f32 v204, v68, v204, v92
	v_fma_f32 v205, v69, v205, v93
	ds_write_b128 v248, v[202:205] offset:4096
	v_sub_f32_e32 v54, v54, v211
	v_sub_f32_e32 v55, v55, v211
	v_sub_f32_e32 v56, v56, v211
	v_sub_f32_e32 v57, v57, v211
	v_mul_f32_e32 v54, v215, v54
	v_mul_f32_e32 v55, v215, v55
	v_mul_f32_e32 v56, v215, v56
	v_mul_f32_e32 v57, v215, v57
	v_fma_f32 v54, v74, v54, v94
	v_fma_f32 v55, v75, v55, v95
	v_fma_f32 v56, v76, v56, v96
	v_fma_f32 v57, v77, v57, v97
	ds_write_b128 v248, v[54:57] offset:4160
	v_sub_f32_e32 v58, v58, v211
	v_sub_f32_e32 v59, v59, v211
	v_sub_f32_e32 v60, v60, v211
	v_sub_f32_e32 v61, v61, v211
	v_mul_f32_e32 v58, v215, v58
	v_mul_f32_e32 v59, v215, v59
	v_mul_f32_e32 v60, v215, v60
	v_mul_f32_e32 v61, v215, v61
	v_fma_f32 v58, v78, v58, v108
	v_fma_f32 v59, v79, v59, v109
	v_fma_f32 v60, v80, v60, v110
	v_fma_f32 v61, v81, v61, v111
	ds_write_b128 v248, v[58:61] offset:4224
	v_sub_f32_e32 v34, v34, v211
	v_sub_f32_e32 v35, v35, v211
	v_sub_f32_e32 v36, v36, v211
	v_sub_f32_e32 v37, v37, v211
	v_mul_f32_e32 v34, v215, v34
	v_mul_f32_e32 v35, v215, v35
	v_mul_f32_e32 v36, v215, v36
	v_mul_f32_e32 v37, v215, v37
	v_fma_f32 v34, v82, v34, v172
	v_fma_f32 v35, v83, v35, v173
	v_fma_f32 v36, v84, v36, v174
	v_fma_f32 v37, v85, v37, v175
	ds_write_b128 v248, v[34:37] offset:4288
	v_sub_f32_e32 v30, v30, v212
	v_sub_f32_e32 v31, v31, v212
	v_sub_f32_e32 v32, v32, v212
	v_sub_f32_e32 v33, v33, v212
	v_mul_f32_e32 v30, v216, v30
	v_mul_f32_e32 v31, v216, v31
	v_mul_f32_e32 v32, v216, v32
	v_mul_f32_e32 v33, v216, v33
	v_fma_f32 v30, v66, v30, v90
	v_fma_f32 v31, v67, v31, v91
	v_fma_f32 v32, v68, v32, v92
	v_fma_f32 v33, v69, v33, v93
	ds_write_b128 v248, v[30:33] offset:8192
	v_sub_f32_e32 v26, v26, v212
	v_sub_f32_e32 v27, v27, v212
	v_sub_f32_e32 v28, v28, v212
	v_sub_f32_e32 v29, v29, v212
	v_mul_f32_e32 v26, v216, v26
	v_mul_f32_e32 v27, v216, v27
	v_mul_f32_e32 v28, v216, v28
	v_mul_f32_e32 v29, v216, v29
	v_fma_f32 v26, v74, v26, v94
	v_fma_f32 v27, v75, v27, v95
	v_fma_f32 v28, v76, v28, v96
	v_fma_f32 v29, v77, v29, v97
	ds_write_b128 v248, v[26:29] offset:8256
	v_sub_f32_e32 v22, v22, v212
	v_sub_f32_e32 v23, v23, v212
	v_sub_f32_e32 v24, v24, v212
	v_sub_f32_e32 v25, v25, v212
	v_mul_f32_e32 v22, v216, v22
	v_mul_f32_e32 v23, v216, v23
	v_mul_f32_e32 v24, v216, v24
	v_mul_f32_e32 v25, v216, v25
	v_fma_f32 v22, v78, v22, v108
	v_fma_f32 v23, v79, v23, v109
	v_fma_f32 v24, v80, v24, v110
	v_fma_f32 v25, v81, v25, v111
	ds_write_b128 v248, v[22:25] offset:8320
	v_sub_f32_e32 v18, v18, v212
	v_sub_f32_e32 v19, v19, v212
	v_sub_f32_e32 v20, v20, v212
	v_sub_f32_e32 v21, v21, v212
	v_mul_f32_e32 v18, v216, v18
	v_mul_f32_e32 v19, v216, v19
	v_mul_f32_e32 v20, v216, v20
	v_mul_f32_e32 v21, v216, v21
	v_fma_f32 v18, v82, v18, v172
	v_fma_f32 v19, v83, v19, v173
	v_fma_f32 v20, v84, v20, v174
	v_fma_f32 v21, v85, v21, v175
	ds_write_b128 v248, v[18:21] offset:8384
	v_sub_f32_e32 v14, v14, v213
	v_sub_f32_e32 v15, v15, v213
	v_sub_f32_e32 v16, v16, v213
	v_sub_f32_e32 v17, v17, v213
	v_mul_f32_e32 v14, v217, v14
	v_mul_f32_e32 v15, v217, v15
	v_mul_f32_e32 v16, v217, v16
	v_mul_f32_e32 v17, v217, v17
	v_fma_f32 v14, v66, v14, v90
	v_fma_f32 v15, v67, v15, v91
	v_fma_f32 v16, v68, v16, v92
	v_fma_f32 v17, v69, v17, v93
	ds_write_b128 v248, v[14:17] offset:12288
	v_sub_f32_e32 v10, v10, v213
	v_sub_f32_e32 v11, v11, v213
	v_sub_f32_e32 v12, v12, v213
	v_sub_f32_e32 v13, v13, v213
	v_mul_f32_e32 v10, v217, v10
	v_mul_f32_e32 v11, v217, v11
	v_mul_f32_e32 v12, v217, v12
	v_mul_f32_e32 v13, v217, v13
	v_fma_f32 v10, v74, v10, v94
	v_fma_f32 v11, v75, v11, v95
	v_fma_f32 v12, v76, v12, v96
	v_fma_f32 v13, v77, v13, v97
	ds_write_b128 v248, v[10:13] offset:12352
	v_sub_f32_e32 v6, v6, v213
	v_sub_f32_e32 v7, v7, v213
	v_sub_f32_e32 v8, v8, v213
	v_sub_f32_e32 v9, v9, v213
	v_mul_f32_e32 v6, v217, v6
	v_mul_f32_e32 v7, v217, v7
	v_mul_f32_e32 v8, v217, v8
	v_mul_f32_e32 v9, v217, v9
	v_fma_f32 v6, v78, v6, v108
	v_fma_f32 v7, v79, v7, v109
	v_fma_f32 v8, v80, v8, v110
	v_fma_f32 v9, v81, v9, v111
	ds_write_b128 v248, v[6:9] offset:12416
	v_sub_f32_e32 v2, v2, v213
	v_sub_f32_e32 v3, v3, v213
	v_sub_f32_e32 v4, v4, v213
	v_sub_f32_e32 v5, v5, v213
	v_mul_f32_e32 v2, v217, v2
	v_mul_f32_e32 v3, v217, v3
	v_mul_f32_e32 v4, v217, v4
	v_mul_f32_e32 v5, v217, v5
	v_fma_f32 v2, v82, v2, v172
	v_fma_f32 v3, v83, v3, v173
	v_fma_f32 v4, v84, v4, v174
	v_fma_f32 v5, v85, v5, v175
	ds_write_b128 v248, v[2:5] offset:12480
	s_waitcnt lgkmcnt(0)
	ds_read_b128 v[66:69], v249 offset:0
	ds_read_b128 v[74:77], v249 offset:1024
	ds_read_b128 v[78:81], v249 offset:2048
	ds_read_b128 v[82:85], v249 offset:3072
	ds_read_b128 v[90:93], v249 offset:4096
	ds_read_b128 v[94:97], v249 offset:5120
	ds_read_b128 v[108:111], v249 offset:6144
	ds_read_b128 v[172:175], v249 offset:7168
	s_waitcnt lgkmcnt(7)
	global_store_dwordx4 v250, v[66:69], s[26:27]
	s_waitcnt lgkmcnt(6)
	v_add_u32_e32 v251, 0x4000, v250
	global_store_dwordx4 v251, v[74:77], s[26:27]
	s_waitcnt lgkmcnt(5)
	v_add_u32_e32 v251, 0x8000, v250
	global_store_dwordx4 v251, v[78:81], s[26:27]
	s_waitcnt lgkmcnt(4)
	v_add_u32_e32 v251, 0xc000, v250
	global_store_dwordx4 v251, v[82:85], s[26:27]
	s_waitcnt lgkmcnt(3)
	v_add_u32_e32 v251, 0x10000, v250
	global_store_dwordx4 v251, v[90:93], s[26:27]
	s_waitcnt lgkmcnt(2)
	v_add_u32_e32 v251, 0x14000, v250
	global_store_dwordx4 v251, v[94:97], s[26:27]
	s_waitcnt lgkmcnt(1)
	v_add_u32_e32 v251, 0x18000, v250
	global_store_dwordx4 v251, v[108:111], s[26:27]
	s_waitcnt lgkmcnt(0)
	v_add_u32_e32 v251, 0x1c000, v250
	global_store_dwordx4 v251, v[172:175], s[26:27]
	s_nop 1
	ds_read_b128 v[66:69], v249 offset:8192
	ds_read_b128 v[74:77], v249 offset:9216
	ds_read_b128 v[78:81], v249 offset:10240
	ds_read_b128 v[82:85], v249 offset:11264
	ds_read_b128 v[90:93], v249 offset:12288
	ds_read_b128 v[94:97], v249 offset:13312
	ds_read_b128 v[108:111], v249 offset:14336
	ds_read_b128 v[172:175], v249 offset:15360
	s_waitcnt lgkmcnt(7)
	v_add_u32_e32 v251, 0x20000, v250
	global_store_dwordx4 v251, v[66:69], s[26:27]
	s_waitcnt lgkmcnt(6)
	v_add_u32_e32 v251, 0x24000, v250
	global_store_dwordx4 v251, v[74:77], s[26:27]
	s_waitcnt lgkmcnt(5)
	v_add_u32_e32 v251, 0x28000, v250
	global_store_dwordx4 v251, v[78:81], s[26:27]
	s_waitcnt lgkmcnt(4)
	v_add_u32_e32 v251, 0x2c000, v250
	global_store_dwordx4 v251, v[82:85], s[26:27]
	s_waitcnt lgkmcnt(3)
	v_add_u32_e32 v251, 0x30000, v250
	global_store_dwordx4 v251, v[90:93], s[26:27]
	s_waitcnt lgkmcnt(2)
	v_add_u32_e32 v251, 0x34000, v250
	global_store_dwordx4 v251, v[94:97], s[26:27]
	s_waitcnt lgkmcnt(1)
	v_add_u32_e32 v251, 0x38000, v250
	global_store_dwordx4 v251, v[108:111], s[26:27]
	s_waitcnt lgkmcnt(0)
	v_add_u32_e32 v251, 0x3c000, v250
	global_store_dwordx4 v251, v[172:175], s[26:27]
	s_nop 1
	s_add_u32 s44, s94, 0x7b48000
	s_addc_u32 s45, s95, 0
	s_waitcnt vmcnt(16)
	v_add_f32_e32 v226, 1.0, v226
	v_add_f32_e32 v227, 1.0, v227
	v_add_f32_e32 v228, 1.0, v228
	v_add_f32_e32 v229, 1.0, v229
	v_add_f32_e32 v230, 1.0, v230
	v_add_f32_e32 v231, 1.0, v231
	v_add_f32_e32 v232, 1.0, v232
	v_add_f32_e32 v233, 1.0, v233
	v_add_f32_e32 v234, 1.0, v234
	v_add_f32_e32 v235, 1.0, v235
	v_add_f32_e32 v236, 1.0, v236
	v_add_f32_e32 v237, 1.0, v237
	v_add_f32_e32 v238, 1.0, v238
	v_add_f32_e32 v239, 1.0, v239
	v_add_f32_e32 v240, 1.0, v240
	v_add_f32_e32 v241, 1.0, v241
	v_and_b32_e32 v251, 7, v246
	v_lshlrev_b32_e32 v251, 1, v251
	v_or_b32_e32 v218, 0, v247
	v_xor_b32_e32 v218, v218, v251
	v_lshlrev_b32_e32 v218, 3, v218
	v_lshl_add_u32 v218, v246, 7, v218
	v_add_u32_e32 v218, s64, v218
	v_or_b32_e32 v219, 4, v247
	v_xor_b32_e32 v219, v219, v251
	v_lshlrev_b32_e32 v219, 3, v219
	v_lshl_add_u32 v219, v246, 7, v219
	v_add_u32_e32 v219, s64, v219
	v_or_b32_e32 v220, 8, v247
	v_xor_b32_e32 v220, v220, v251
	v_lshlrev_b32_e32 v220, 3, v220
	v_lshl_add_u32 v220, v246, 7, v220
	v_add_u32_e32 v220, s64, v220
	v_or_b32_e32 v221, 12, v247
	v_xor_b32_e32 v221, v221, v251
	v_lshlrev_b32_e32 v221, 3, v221
	v_lshl_add_u32 v221, v246, 7, v221
	v_add_u32_e32 v221, s64, v221
	v_lshrrev_b32_e32 v248, 3, v222
	v_and_b32_e32 v251, 7, v222
	v_xor_b32_e32 v251, v251, v248
	v_add_u32_e32 v248, s36, v248
	v_lshlrev_b32_e32 v248, 11, v248
	v_lshl_add_u32 v248, v251, 4, v248
	s_lshl_b32 s65, s37, 1
	v_add_u32_e32 v248, s65, v248
	v_fma_f32 v62, v226, v62, v38
	v_fma_f32 v63, v227, v63, v39
	v_fma_f32 v64, v228, v64, v40
	v_fma_f32 v65, v229, v65, v41
	v_cvt_pk_bf16_f32 v62, v62, v63
	v_cvt_pk_bf16_f32 v63, v64, v65
	ds_write_b64 v218, v[62:63] offset:0
	v_fma_f32 v86, v230, v86, v42
	v_fma_f32 v87, v231, v87, v43
	v_fma_f32 v88, v232, v88, v44
	v_fma_f32 v89, v233, v89, v45
	v_cvt_pk_bf16_f32 v86, v86, v87
	v_cvt_pk_bf16_f32 v87, v88, v89
	ds_write_b64 v219, v[86:87] offset:0
	v_fma_f32 v70, v234, v70, v46
	v_fma_f32 v71, v235, v71, v47
	v_fma_f32 v72, v236, v72, v48
	v_fma_f32 v73, v237, v73, v49
	v_cvt_pk_bf16_f32 v70, v70, v71
	v_cvt_pk_bf16_f32 v71, v72, v73
	ds_write_b64 v220, v[70:71] offset:0
	v_fma_f32 v176, v238, v176, v50
	v_fma_f32 v177, v239, v177, v51
	v_fma_f32 v178, v240, v178, v52
	v_fma_f32 v179, v241, v179, v53
	v_cvt_pk_bf16_f32 v176, v176, v177
	v_cvt_pk_bf16_f32 v177, v178, v179
	ds_write_b64 v221, v[176:177] offset:0
	v_fma_f32 v202, v226, v202, v38
	v_fma_f32 v203, v227, v203, v39
	v_fma_f32 v204, v228, v204, v40
	v_fma_f32 v205, v229, v205, v41
	v_cvt_pk_bf16_f32 v202, v202, v203
	v_cvt_pk_bf16_f32 v203, v204, v205
	ds_write_b64 v218, v[202:203] offset:2048
	v_fma_f32 v54, v230, v54, v42
	v_fma_f32 v55, v231, v55, v43
	v_fma_f32 v56, v232, v56, v44
	v_fma_f32 v57, v233, v57, v45
	v_cvt_pk_bf16_f32 v54, v54, v55
	v_cvt_pk_bf16_f32 v55, v56, v57
	ds_write_b64 v219, v[54:55] offset:2048
	v_fma_f32 v58, v234, v58, v46
	v_fma_f32 v59, v235, v59, v47
	v_fma_f32 v60, v236, v60, v48
	v_fma_f32 v61, v237, v61, v49
	v_cvt_pk_bf16_f32 v58, v58, v59
	v_cvt_pk_bf16_f32 v59, v60, v61
	ds_write_b64 v220, v[58:59] offset:2048
	v_fma_f32 v34, v238, v34, v50
	v_fma_f32 v35, v239, v35, v51
	v_fma_f32 v36, v240, v36, v52
	v_fma_f32 v37, v241, v37, v53
	v_cvt_pk_bf16_f32 v34, v34, v35
	v_cvt_pk_bf16_f32 v35, v36, v37
	ds_write_b64 v221, v[34:35] offset:2048
	v_fma_f32 v30, v226, v30, v38
	v_fma_f32 v31, v227, v31, v39
	v_fma_f32 v32, v228, v32, v40
	v_fma_f32 v33, v229, v33, v41
	v_cvt_pk_bf16_f32 v30, v30, v31
	v_cvt_pk_bf16_f32 v31, v32, v33
	ds_write_b64 v218, v[30:31] offset:4096
	v_fma_f32 v26, v230, v26, v42
	v_fma_f32 v27, v231, v27, v43
	v_fma_f32 v28, v232, v28, v44
	v_fma_f32 v29, v233, v29, v45
	v_cvt_pk_bf16_f32 v26, v26, v27
	v_cvt_pk_bf16_f32 v27, v28, v29
	ds_write_b64 v219, v[26:27] offset:4096
	v_fma_f32 v22, v234, v22, v46
	v_fma_f32 v23, v235, v23, v47
	v_fma_f32 v24, v236, v24, v48
	v_fma_f32 v25, v237, v25, v49
	v_cvt_pk_bf16_f32 v22, v22, v23
	v_cvt_pk_bf16_f32 v23, v24, v25
	ds_write_b64 v220, v[22:23] offset:4096
	v_fma_f32 v18, v238, v18, v50
	v_fma_f32 v19, v239, v19, v51
	v_fma_f32 v20, v240, v20, v52
	v_fma_f32 v21, v241, v21, v53
	v_cvt_pk_bf16_f32 v18, v18, v19
	v_cvt_pk_bf16_f32 v19, v20, v21
	ds_write_b64 v221, v[18:19] offset:4096
	v_fma_f32 v14, v226, v14, v38
	v_fma_f32 v15, v227, v15, v39
	v_fma_f32 v16, v228, v16, v40
	v_fma_f32 v17, v229, v17, v41
	v_cvt_pk_bf16_f32 v14, v14, v15
	v_cvt_pk_bf16_f32 v15, v16, v17
	ds_write_b64 v218, v[14:15] offset:6144
	v_fma_f32 v10, v230, v10, v42
	v_fma_f32 v11, v231, v11, v43
	v_fma_f32 v12, v232, v12, v44
	v_fma_f32 v13, v233, v13, v45
	v_cvt_pk_bf16_f32 v10, v10, v11
	v_cvt_pk_bf16_f32 v11, v12, v13
	ds_write_b64 v219, v[10:11] offset:6144
	v_fma_f32 v6, v234, v6, v46
	v_fma_f32 v7, v235, v7, v47
	v_fma_f32 v8, v236, v8, v48
	v_fma_f32 v9, v237, v9, v49
	v_cvt_pk_bf16_f32 v6, v6, v7
	v_cvt_pk_bf16_f32 v7, v8, v9
	ds_write_b64 v220, v[6:7] offset:6144
	v_fma_f32 v2, v238, v2, v50
	v_fma_f32 v3, v239, v3, v51
	v_fma_f32 v4, v240, v4, v52
	v_fma_f32 v5, v241, v5, v53
	v_cvt_pk_bf16_f32 v2, v2, v3
	v_cvt_pk_bf16_f32 v3, v4, v5
	ds_write_b64 v221, v[2:3] offset:6144
	s_waitcnt lgkmcnt(0)
	ds_read_b128 v[66:69], v249 offset:0
	ds_read_b128 v[74:77], v249 offset:1024
	ds_read_b128 v[78:81], v249 offset:2048
	ds_read_b128 v[82:85], v249 offset:3072
	ds_read_b128 v[90:93], v249 offset:4096
	ds_read_b128 v[94:97], v249 offset:5120
	ds_read_b128 v[108:111], v249 offset:6144
	ds_read_b128 v[172:175], v249 offset:7168
	s_waitcnt lgkmcnt(7)
	global_store_dwordx4 v248, v[66:69], s[44:45]
	s_waitcnt lgkmcnt(6)
	v_add_u32_e32 v251, 0x4000, v248
	global_store_dwordx4 v251, v[74:77], s[44:45]
	s_waitcnt lgkmcnt(5)
	v_add_u32_e32 v251, 0x8000, v248
	global_store_dwordx4 v251, v[78:81], s[44:45]
	s_waitcnt lgkmcnt(4)
	v_add_u32_e32 v251, 0xc000, v248
	global_store_dwordx4 v251, v[82:85], s[44:45]
	s_waitcnt lgkmcnt(3)
	v_add_u32_e32 v251, 0x10000, v248
	global_store_dwordx4 v251, v[90:93], s[44:45]
	s_waitcnt lgkmcnt(2)
	v_add_u32_e32 v251, 0x14000, v248
	global_store_dwordx4 v251, v[94:97], s[44:45]
	s_waitcnt lgkmcnt(1)
	v_add_u32_e32 v251, 0x18000, v248
	global_store_dwordx4 v251, v[108:111], s[44:45]
	s_waitcnt lgkmcnt(0)
	v_add_u32_e32 v251, 0x1c000, v248
	global_store_dwordx4 v251, v[172:175], s[44:45]
	v_readlane_b32 s78, v255, 33
	v_readlane_b32 s79, v255, 34
	s_barrier
	s_load_dword s6, s[78:79], 0x0
	s_mov_b64 s[76:77], 0x7b4c180
	s_mov_b64 s[68:69], 0x7b54180
	s_mov_b64 s[74:75], 0x68800
	s_waitcnt lgkmcnt(0)
	s_add_i32 s60, s6, s60
	s_cmpk_gt_i32 s60, 0xbf
	s_cbranch_scc0 .LBB0_93

.Lln2_nomod:
	v_mov_b32_e32 v206, v250
	v_mov_b32_e32 v207, v252
	v_mul_f32_e32 v208, 0x3a800000, v206
	v_mul_f32_e32 v209, v208, v208
	v_mov_b32_e32 v216, 0x3a800000
	v_fma_f32 v209, v207, v216, -v209
	v_max_f32_e32 v209, 0, v209
	v_add_f32_e32 v209, 0x3727c5ac, v209
	v_rsq_f32_e32 v209, v209
	v_mov_b32_e32 v210, v208
	v_mov_b32_e32 v211, v208
	v_mov_b32_e32 v214, v209
	v_mov_b32_e32 v215, v209
	s_nop 1
	v_permlane16_swap_b32_e32 v210, v211
	v_permlane16_swap_b32_e32 v214, v215
	v_mov_b32_e32 v212, v210
	v_mov_b32_e32 v213, v211
	v_mov_b32_e32 v216, v214
	v_mov_b32_e32 v217, v215
	s_nop 1
	v_permlane32_swap_b32_e32 v210, v212
	v_permlane32_swap_b32_e32 v211, v213
	v_permlane32_swap_b32_e32 v214, v216
	v_permlane32_swap_b32_e32 v215, v217
	s_cmp_eq_u32 s53, 3
	s_cselect_b32 s26, s92, s26
	s_cselect_b32 s27, s93, s27
	v_readfirstlane_b32 s54, v137
	s_lshr_b32 s54, s54, 6
	s_lshl_b32 s54, s54, 14
	v_and_b32_e32 v222, 63, v137
	v_and_b32_e32 v246, 15, v222
	v_lshrrev_b32_e32 v247, 4, v222
	v_and_b32_e32 v248, 3, v246
	v_xor_b32_e32 v248, v248, v247
	v_lshlrev_b32_e32 v248, 4, v248
	v_lshl_add_u32 v248, v246, 8, v248
	v_add_u32_e32 v248, s54, v248
	v_lshl_add_u32 v249, v222, 4, s54
	v_add_u32_e32 v250, s50, v247
	v_lshlrev_b32_e32 v250, 12, v250
	v_xor_b32_e32 v251, v246, v247
	v_lshl_add_u32 v250, v251, 4, v250
	s_lshl_b32 s55, s51, 2
	v_add_u32_e32 v250, s55, v250
	v_sub_f32_e32 v62, v62, v210
	v_sub_f32_e32 v63, v63, v210
	v_sub_f32_e32 v64, v64, v210
	v_sub_f32_e32 v65, v65, v210
	v_mul_f32_e32 v62, v214, v62
	v_mul_f32_e32 v63, v214, v63
	v_mul_f32_e32 v64, v214, v64
	v_mul_f32_e32 v65, v214, v65
	v_fma_f32 v62, v66, v62, v90
	v_fma_f32 v63, v67, v63, v91
	v_fma_f32 v64, v68, v64, v92
	v_fma_f32 v65, v69, v65, v93
	ds_write_b128 v248, v[62:65] offset:0
	v_sub_f32_e32 v86, v86, v210
	v_sub_f32_e32 v87, v87, v210
	v_sub_f32_e32 v88, v88, v210
	v_sub_f32_e32 v89, v89, v210
	v_mul_f32_e32 v86, v214, v86
	v_mul_f32_e32 v87, v214, v87
	v_mul_f32_e32 v88, v214, v88
	v_mul_f32_e32 v89, v214, v89
	v_fma_f32 v86, v74, v86, v94
	v_fma_f32 v87, v75, v87, v95
	v_fma_f32 v88, v76, v88, v96
	v_fma_f32 v89, v77, v89, v97
	ds_write_b128 v248, v[86:89] offset:64
	v_sub_f32_e32 v70, v70, v210
	v_sub_f32_e32 v71, v71, v210
	v_sub_f32_e32 v72, v72, v210
	v_sub_f32_e32 v73, v73, v210
	v_mul_f32_e32 v70, v214, v70
	v_mul_f32_e32 v71, v214, v71
	v_mul_f32_e32 v72, v214, v72
	v_mul_f32_e32 v73, v214, v73
	v_fma_f32 v70, v78, v70, v108
	v_fma_f32 v71, v79, v71, v109
	v_fma_f32 v72, v80, v72, v110
	v_fma_f32 v73, v81, v73, v111
	ds_write_b128 v248, v[70:73] offset:128
	v_sub_f32_e32 v176, v176, v210
	v_sub_f32_e32 v177, v177, v210
	v_sub_f32_e32 v178, v178, v210
	v_sub_f32_e32 v179, v179, v210
	v_mul_f32_e32 v176, v214, v176
	v_mul_f32_e32 v177, v214, v177
	v_mul_f32_e32 v178, v214, v178
	v_mul_f32_e32 v179, v214, v179
	v_fma_f32 v176, v82, v176, v172
	v_fma_f32 v177, v83, v177, v173
	v_fma_f32 v178, v84, v178, v174
	v_fma_f32 v179, v85, v179, v175
	ds_write_b128 v248, v[176:179] offset:192
	v_sub_f32_e32 v202, v202, v211
	v_sub_f32_e32 v203, v203, v211
	v_sub_f32_e32 v204, v204, v211
	v_sub_f32_e32 v205, v205, v211
	v_mul_f32_e32 v202, v215, v202
	v_mul_f32_e32 v203, v215, v203
	v_mul_f32_e32 v204, v215, v204
	v_mul_f32_e32 v205, v215, v205
	v_fma_f32 v202, v66, v202, v90
	v_fma_f32 v203, v67, v203, v91
	v_fma_f32 v204, v68, v204, v92
	v_fma_f32 v205, v69, v205, v93
	ds_write_b128 v248, v[202:205] offset:4096
	v_sub_f32_e32 v54, v54, v211
	v_sub_f32_e32 v55, v55, v211
	v_sub_f32_e32 v56, v56, v211
	v_sub_f32_e32 v57, v57, v211
	v_mul_f32_e32 v54, v215, v54
	v_mul_f32_e32 v55, v215, v55
	v_mul_f32_e32 v56, v215, v56
	v_mul_f32_e32 v57, v215, v57
	v_fma_f32 v54, v74, v54, v94
	v_fma_f32 v55, v75, v55, v95
	v_fma_f32 v56, v76, v56, v96
	v_fma_f32 v57, v77, v57, v97
	ds_write_b128 v248, v[54:57] offset:4160
	v_sub_f32_e32 v58, v58, v211
	v_sub_f32_e32 v59, v59, v211
	v_sub_f32_e32 v60, v60, v211
	v_sub_f32_e32 v61, v61, v211
	v_mul_f32_e32 v58, v215, v58
	v_mul_f32_e32 v59, v215, v59
	v_mul_f32_e32 v60, v215, v60
	v_mul_f32_e32 v61, v215, v61
	v_fma_f32 v58, v78, v58, v108
	v_fma_f32 v59, v79, v59, v109
	v_fma_f32 v60, v80, v60, v110
	v_fma_f32 v61, v81, v61, v111
	ds_write_b128 v248, v[58:61] offset:4224
	v_sub_f32_e32 v34, v34, v211
	v_sub_f32_e32 v35, v35, v211
	v_sub_f32_e32 v36, v36, v211
	v_sub_f32_e32 v37, v37, v211
	v_mul_f32_e32 v34, v215, v34
	v_mul_f32_e32 v35, v215, v35
	v_mul_f32_e32 v36, v215, v36
	v_mul_f32_e32 v37, v215, v37
	v_fma_f32 v34, v82, v34, v172
	v_fma_f32 v35, v83, v35, v173
	v_fma_f32 v36, v84, v36, v174
	v_fma_f32 v37, v85, v37, v175
	ds_write_b128 v248, v[34:37] offset:4288
	v_sub_f32_e32 v30, v30, v212
	v_sub_f32_e32 v31, v31, v212
	v_sub_f32_e32 v32, v32, v212
	v_sub_f32_e32 v33, v33, v212
	v_mul_f32_e32 v30, v216, v30
	v_mul_f32_e32 v31, v216, v31
	v_mul_f32_e32 v32, v216, v32
	v_mul_f32_e32 v33, v216, v33
	v_fma_f32 v30, v66, v30, v90
	v_fma_f32 v31, v67, v31, v91
	v_fma_f32 v32, v68, v32, v92
	v_fma_f32 v33, v69, v33, v93
	ds_write_b128 v248, v[30:33] offset:8192
	v_sub_f32_e32 v26, v26, v212
	v_sub_f32_e32 v27, v27, v212
	v_sub_f32_e32 v28, v28, v212
	v_sub_f32_e32 v29, v29, v212
	v_mul_f32_e32 v26, v216, v26
	v_mul_f32_e32 v27, v216, v27
	v_mul_f32_e32 v28, v216, v28
	v_mul_f32_e32 v29, v216, v29
	v_fma_f32 v26, v74, v26, v94
	v_fma_f32 v27, v75, v27, v95
	v_fma_f32 v28, v76, v28, v96
	v_fma_f32 v29, v77, v29, v97
	ds_write_b128 v248, v[26:29] offset:8256
	v_sub_f32_e32 v22, v22, v212
	v_sub_f32_e32 v23, v23, v212
	v_sub_f32_e32 v24, v24, v212
	v_sub_f32_e32 v25, v25, v212
	v_mul_f32_e32 v22, v216, v22
	v_mul_f32_e32 v23, v216, v23
	v_mul_f32_e32 v24, v216, v24
	v_mul_f32_e32 v25, v216, v25
	v_fma_f32 v22, v78, v22, v108
	v_fma_f32 v23, v79, v23, v109
	v_fma_f32 v24, v80, v24, v110
	v_fma_f32 v25, v81, v25, v111
	ds_write_b128 v248, v[22:25] offset:8320
	v_sub_f32_e32 v18, v18, v212
	v_sub_f32_e32 v19, v19, v212
	v_sub_f32_e32 v20, v20, v212
	v_sub_f32_e32 v21, v21, v212
	v_mul_f32_e32 v18, v216, v18
	v_mul_f32_e32 v19, v216, v19
	v_mul_f32_e32 v20, v216, v20
	v_mul_f32_e32 v21, v216, v21
	v_fma_f32 v18, v82, v18, v172
	v_fma_f32 v19, v83, v19, v173
	v_fma_f32 v20, v84, v20, v174
	v_fma_f32 v21, v85, v21, v175
	ds_write_b128 v248, v[18:21] offset:8384
	v_sub_f32_e32 v14, v14, v213
	v_sub_f32_e32 v15, v15, v213
	v_sub_f32_e32 v16, v16, v213
	v_sub_f32_e32 v17, v17, v213
	v_mul_f32_e32 v14, v217, v14
	v_mul_f32_e32 v15, v217, v15
	v_mul_f32_e32 v16, v217, v16
	v_mul_f32_e32 v17, v217, v17
	v_fma_f32 v14, v66, v14, v90
	v_fma_f32 v15, v67, v15, v91
	v_fma_f32 v16, v68, v16, v92
	v_fma_f32 v17, v69, v17, v93
	ds_write_b128 v248, v[14:17] offset:12288
	v_sub_f32_e32 v10, v10, v213
	v_sub_f32_e32 v11, v11, v213
	v_sub_f32_e32 v12, v12, v213
	v_sub_f32_e32 v13, v13, v213
	v_mul_f32_e32 v10, v217, v10
	v_mul_f32_e32 v11, v217, v11
	v_mul_f32_e32 v12, v217, v12
	v_mul_f32_e32 v13, v217, v13
	v_fma_f32 v10, v74, v10, v94
	v_fma_f32 v11, v75, v11, v95
	v_fma_f32 v12, v76, v12, v96
	v_fma_f32 v13, v77, v13, v97
	ds_write_b128 v248, v[10:13] offset:12352
	v_sub_f32_e32 v6, v6, v213
	v_sub_f32_e32 v7, v7, v213
	v_sub_f32_e32 v8, v8, v213
	v_sub_f32_e32 v9, v9, v213
	v_mul_f32_e32 v6, v217, v6
	v_mul_f32_e32 v7, v217, v7
	v_mul_f32_e32 v8, v217, v8
	v_mul_f32_e32 v9, v217, v9
	v_fma_f32 v6, v78, v6, v108
	v_fma_f32 v7, v79, v7, v109
	v_fma_f32 v8, v80, v8, v110
	v_fma_f32 v9, v81, v9, v111
	ds_write_b128 v248, v[6:9] offset:12416
	v_sub_f32_e32 v2, v2, v213
	v_sub_f32_e32 v3, v3, v213
	v_sub_f32_e32 v4, v4, v213
	v_sub_f32_e32 v5, v5, v213
	v_mul_f32_e32 v2, v217, v2
	v_mul_f32_e32 v3, v217, v3
	v_mul_f32_e32 v4, v217, v4
	v_mul_f32_e32 v5, v217, v5
	v_fma_f32 v2, v82, v2, v172
	v_fma_f32 v3, v83, v3, v173
	v_fma_f32 v4, v84, v4, v174
	v_fma_f32 v5, v85, v5, v175
	ds_write_b128 v248, v[2:5] offset:12480
	s_waitcnt lgkmcnt(0)
	ds_read_b128 v[66:69], v249 offset:0
	ds_read_b128 v[74:77], v249 offset:1024
	ds_read_b128 v[78:81], v249 offset:2048
	ds_read_b128 v[82:85], v249 offset:3072
	ds_read_b128 v[90:93], v249 offset:4096
	ds_read_b128 v[94:97], v249 offset:5120
	ds_read_b128 v[108:111], v249 offset:6144
	ds_read_b128 v[172:175], v249 offset:7168
	s_waitcnt lgkmcnt(7)
	global_store_dwordx4 v250, v[66:69], s[26:27]
	s_waitcnt lgkmcnt(6)
	v_add_u32_e32 v251, 0x4000, v250
	global_store_dwordx4 v251, v[74:77], s[26:27]
	s_waitcnt lgkmcnt(5)
	v_add_u32_e32 v251, 0x8000, v250
	global_store_dwordx4 v251, v[78:81], s[26:27]
	s_waitcnt lgkmcnt(4)
	v_add_u32_e32 v251, 0xc000, v250
	global_store_dwordx4 v251, v[82:85], s[26:27]
	s_waitcnt lgkmcnt(3)
	v_add_u32_e32 v251, 0x10000, v250
	global_store_dwordx4 v251, v[90:93], s[26:27]
	s_waitcnt lgkmcnt(2)
	v_add_u32_e32 v251, 0x14000, v250
	global_store_dwordx4 v251, v[94:97], s[26:27]
	s_waitcnt lgkmcnt(1)
	v_add_u32_e32 v251, 0x18000, v250
	global_store_dwordx4 v251, v[108:111], s[26:27]
	s_waitcnt lgkmcnt(0)
	v_add_u32_e32 v251, 0x1c000, v250
	global_store_dwordx4 v251, v[172:175], s[26:27]
	s_nop 1
	ds_read_b128 v[66:69], v249 offset:8192
	ds_read_b128 v[74:77], v249 offset:9216
	ds_read_b128 v[78:81], v249 offset:10240
	ds_read_b128 v[82:85], v249 offset:11264
	ds_read_b128 v[90:93], v249 offset:12288
	ds_read_b128 v[94:97], v249 offset:13312
	ds_read_b128 v[108:111], v249 offset:14336
	ds_read_b128 v[172:175], v249 offset:15360
	s_waitcnt lgkmcnt(7)
	v_add_u32_e32 v251, 0x20000, v250
	global_store_dwordx4 v251, v[66:69], s[26:27]
	s_waitcnt lgkmcnt(6)
	v_add_u32_e32 v251, 0x24000, v250
	global_store_dwordx4 v251, v[74:77], s[26:27]
	s_waitcnt lgkmcnt(5)
	v_add_u32_e32 v251, 0x28000, v250
	global_store_dwordx4 v251, v[78:81], s[26:27]
	s_waitcnt lgkmcnt(4)
	v_add_u32_e32 v251, 0x2c000, v250
	global_store_dwordx4 v251, v[82:85], s[26:27]
	s_waitcnt lgkmcnt(3)
	v_add_u32_e32 v251, 0x30000, v250
	global_store_dwordx4 v251, v[90:93], s[26:27]
	s_waitcnt lgkmcnt(2)
	v_add_u32_e32 v251, 0x34000, v250
	global_store_dwordx4 v251, v[94:97], s[26:27]
	s_waitcnt lgkmcnt(1)
	v_add_u32_e32 v251, 0x38000, v250
	global_store_dwordx4 v251, v[108:111], s[26:27]
	s_waitcnt lgkmcnt(0)
	v_add_u32_e32 v251, 0x3c000, v250
	global_store_dwordx4 v251, v[172:175], s[26:27]
	s_nop 1
	s_cmp_eq_u32 s53, 3
	s_cbranch_scc1 .Lln2_end
	s_add_u32 s34, s94, 0x7b48000
	s_addc_u32 s35, s95, 0
	s_waitcnt vmcnt(16)
	v_add_f32_e32 v226, 1.0, v226
	v_add_f32_e32 v227, 1.0, v227
	v_add_f32_e32 v228, 1.0, v228
	v_add_f32_e32 v229, 1.0, v229
	v_add_f32_e32 v230, 1.0, v230
	v_add_f32_e32 v231, 1.0, v231
	v_add_f32_e32 v232, 1.0, v232
	v_add_f32_e32 v233, 1.0, v233
	v_add_f32_e32 v234, 1.0, v234
	v_add_f32_e32 v235, 1.0, v235
	v_add_f32_e32 v236, 1.0, v236
	v_add_f32_e32 v237, 1.0, v237
	v_add_f32_e32 v238, 1.0, v238
	v_add_f32_e32 v239, 1.0, v239
	v_add_f32_e32 v240, 1.0, v240
	v_add_f32_e32 v241, 1.0, v241
	v_and_b32_e32 v251, 7, v246
	v_lshlrev_b32_e32 v251, 1, v251
	v_or_b32_e32 v218, 0, v247
	v_xor_b32_e32 v218, v218, v251
	v_lshlrev_b32_e32 v218, 3, v218
	v_lshl_add_u32 v218, v246, 7, v218
	v_add_u32_e32 v218, s54, v218
	v_or_b32_e32 v219, 4, v247
	v_xor_b32_e32 v219, v219, v251
	v_lshlrev_b32_e32 v219, 3, v219
	v_lshl_add_u32 v219, v246, 7, v219
	v_add_u32_e32 v219, s54, v219
	v_or_b32_e32 v220, 8, v247
	v_xor_b32_e32 v220, v220, v251
	v_lshlrev_b32_e32 v220, 3, v220
	v_lshl_add_u32 v220, v246, 7, v220
	v_add_u32_e32 v220, s54, v220
	v_or_b32_e32 v221, 12, v247
	v_xor_b32_e32 v221, v221, v251
	v_lshlrev_b32_e32 v221, 3, v221
	v_lshl_add_u32 v221, v246, 7, v221
	v_add_u32_e32 v221, s54, v221
	v_lshrrev_b32_e32 v248, 3, v222
	v_and_b32_e32 v251, 7, v222
	v_xor_b32_e32 v251, v251, v248
	v_add_u32_e32 v248, s50, v248
	v_lshlrev_b32_e32 v248, 11, v248
	v_lshl_add_u32 v248, v251, 4, v248
	s_lshl_b32 s55, s51, 1
	v_add_u32_e32 v248, s55, v248
	v_fma_f32 v62, v226, v62, v38
	v_fma_f32 v63, v227, v63, v39
	v_fma_f32 v64, v228, v64, v40
	v_fma_f32 v65, v229, v65, v41
	v_cvt_pk_bf16_f32 v62, v62, v63
	v_cvt_pk_bf16_f32 v63, v64, v65
	ds_write_b64 v218, v[62:63] offset:0
	v_fma_f32 v86, v230, v86, v42
	v_fma_f32 v87, v231, v87, v43
	v_fma_f32 v88, v232, v88, v44
	v_fma_f32 v89, v233, v89, v45
	v_cvt_pk_bf16_f32 v86, v86, v87
	v_cvt_pk_bf16_f32 v87, v88, v89
	ds_write_b64 v219, v[86:87] offset:0
	v_fma_f32 v70, v234, v70, v46
	v_fma_f32 v71, v235, v71, v47
	v_fma_f32 v72, v236, v72, v48
	v_fma_f32 v73, v237, v73, v49
	v_cvt_pk_bf16_f32 v70, v70, v71
	v_cvt_pk_bf16_f32 v71, v72, v73
	ds_write_b64 v220, v[70:71] offset:0
	v_fma_f32 v176, v238, v176, v50
	v_fma_f32 v177, v239, v177, v51
	v_fma_f32 v178, v240, v178, v52
	v_fma_f32 v179, v241, v179, v53
	v_cvt_pk_bf16_f32 v176, v176, v177
	v_cvt_pk_bf16_f32 v177, v178, v179
	ds_write_b64 v221, v[176:177] offset:0
	v_fma_f32 v202, v226, v202, v38
	v_fma_f32 v203, v227, v203, v39
	v_fma_f32 v204, v228, v204, v40
	v_fma_f32 v205, v229, v205, v41
	v_cvt_pk_bf16_f32 v202, v202, v203
	v_cvt_pk_bf16_f32 v203, v204, v205
	ds_write_b64 v218, v[202:203] offset:2048
	v_fma_f32 v54, v230, v54, v42
	v_fma_f32 v55, v231, v55, v43
	v_fma_f32 v56, v232, v56, v44
	v_fma_f32 v57, v233, v57, v45
	v_cvt_pk_bf16_f32 v54, v54, v55
	v_cvt_pk_bf16_f32 v55, v56, v57
	ds_write_b64 v219, v[54:55] offset:2048
	v_fma_f32 v58, v234, v58, v46
	v_fma_f32 v59, v235, v59, v47
	v_fma_f32 v60, v236, v60, v48
	v_fma_f32 v61, v237, v61, v49
	v_cvt_pk_bf16_f32 v58, v58, v59
	v_cvt_pk_bf16_f32 v59, v60, v61
	ds_write_b64 v220, v[58:59] offset:2048
	v_fma_f32 v34, v238, v34, v50
	v_fma_f32 v35, v239, v35, v51
	v_fma_f32 v36, v240, v36, v52
	v_fma_f32 v37, v241, v37, v53
	v_cvt_pk_bf16_f32 v34, v34, v35
	v_cvt_pk_bf16_f32 v35, v36, v37
	ds_write_b64 v221, v[34:35] offset:2048
	v_fma_f32 v30, v226, v30, v38
	v_fma_f32 v31, v227, v31, v39
	v_fma_f32 v32, v228, v32, v40
	v_fma_f32 v33, v229, v33, v41
	v_cvt_pk_bf16_f32 v30, v30, v31
	v_cvt_pk_bf16_f32 v31, v32, v33
	ds_write_b64 v218, v[30:31] offset:4096
	v_fma_f32 v26, v230, v26, v42
	v_fma_f32 v27, v231, v27, v43
	v_fma_f32 v28, v232, v28, v44
	v_fma_f32 v29, v233, v29, v45
	v_cvt_pk_bf16_f32 v26, v26, v27
	v_cvt_pk_bf16_f32 v27, v28, v29
	ds_write_b64 v219, v[26:27] offset:4096
	v_fma_f32 v22, v234, v22, v46
	v_fma_f32 v23, v235, v23, v47
	v_fma_f32 v24, v236, v24, v48
	v_fma_f32 v25, v237, v25, v49
	v_cvt_pk_bf16_f32 v22, v22, v23
	v_cvt_pk_bf16_f32 v23, v24, v25
	ds_write_b64 v220, v[22:23] offset:4096
	v_fma_f32 v18, v238, v18, v50
	v_fma_f32 v19, v239, v19, v51
	v_fma_f32 v20, v240, v20, v52
	v_fma_f32 v21, v241, v21, v53
	v_cvt_pk_bf16_f32 v18, v18, v19
	v_cvt_pk_bf16_f32 v19, v20, v21
	ds_write_b64 v221, v[18:19] offset:4096
	v_fma_f32 v14, v226, v14, v38
	v_fma_f32 v15, v227, v15, v39
	v_fma_f32 v16, v228, v16, v40
	v_fma_f32 v17, v229, v17, v41
	v_cvt_pk_bf16_f32 v14, v14, v15
	v_cvt_pk_bf16_f32 v15, v16, v17
	ds_write_b64 v218, v[14:15] offset:6144
	v_fma_f32 v10, v230, v10, v42
	v_fma_f32 v11, v231, v11, v43
	v_fma_f32 v12, v232, v12, v44
	v_fma_f32 v13, v233, v13, v45
	v_cvt_pk_bf16_f32 v10, v10, v11
	v_cvt_pk_bf16_f32 v11, v12, v13
	ds_write_b64 v219, v[10:11] offset:6144
	v_fma_f32 v6, v234, v6, v46
	v_fma_f32 v7, v235, v7, v47
	v_fma_f32 v8, v236, v8, v48
	v_fma_f32 v9, v237, v9, v49
	v_cvt_pk_bf16_f32 v6, v6, v7
	v_cvt_pk_bf16_f32 v7, v8, v9
	ds_write_b64 v220, v[6:7] offset:6144
	v_fma_f32 v2, v238, v2, v50
	v_fma_f32 v3, v239, v3, v51
	v_fma_f32 v4, v240, v4, v52
	v_fma_f32 v5, v241, v5, v53
	v_cvt_pk_bf16_f32 v2, v2, v3
	v_cvt_pk_bf16_f32 v3, v4, v5
	ds_write_b64 v221, v[2:3] offset:6144
	s_waitcnt lgkmcnt(0)
	ds_read_b128 v[66:69], v249 offset:0
	ds_read_b128 v[74:77], v249 offset:1024
	ds_read_b128 v[78:81], v249 offset:2048
	ds_read_b128 v[82:85], v249 offset:3072
	ds_read_b128 v[90:93], v249 offset:4096
	ds_read_b128 v[94:97], v249 offset:5120
	ds_read_b128 v[108:111], v249 offset:6144
	ds_read_b128 v[172:175], v249 offset:7168
	s_waitcnt lgkmcnt(7)
	global_store_dwordx4 v248, v[66:69], s[34:35]
	s_waitcnt lgkmcnt(6)
	v_add_u32_e32 v251, 0x4000, v248
	global_store_dwordx4 v251, v[74:77], s[34:35]
	s_waitcnt lgkmcnt(5)
	v_add_u32_e32 v251, 0x8000, v248
	global_store_dwordx4 v251, v[78:81], s[34:35]
	s_waitcnt lgkmcnt(4)
	v_add_u32_e32 v251, 0xc000, v248
	global_store_dwordx4 v251, v[82:85], s[34:35]
	s_waitcnt lgkmcnt(3)
	v_add_u32_e32 v251, 0x10000, v248
	global_store_dwordx4 v251, v[90:93], s[34:35]
	s_waitcnt lgkmcnt(2)
	v_add_u32_e32 v251, 0x14000, v248
	global_store_dwordx4 v251, v[94:97], s[34:35]
	s_waitcnt lgkmcnt(1)
	v_add_u32_e32 v251, 0x18000, v248
	global_store_dwordx4 v251, v[108:111], s[34:35]
	s_waitcnt lgkmcnt(0)
	v_add_u32_e32 v251, 0x1c000, v248
	global_store_dwordx4 v251, v[172:175], s[34:35]
